# scan stage-C loads hoisted out of the unrolled loop + sample-row GEMM units issue all 32 fragment loads up front (5 instances)
# speedup vs baseline: 1.0098x; 1.0022x over previous
.LBB0_665:
	s_lshr_b32 s10, s9, 3
	s_and_b32 s11, s3, 0xe0
	s_lshl_b32 s12, s10, 20
	s_add_u32 s12, s33, s12
	s_addc_u32 s13, s34, 0
	s_lshl_b32 s14, s11, 12
	s_add_u32 s12, s12, s14
	s_addc_u32 s13, s13, 0
	s_add_u32 s12, s12, s0
	s_addc_u32 s13, s13, s1
	v_lshl_add_u64 v[32:33], s[12:13], 0, v[26:27]
	v_lshl_add_u64 v[76:77], v[32:33], 0, v[28:29]
	v_add_co_u32_e32 v78, vcc, s2, v76
	s_nop 1
	v_addc_co_u32_e32 v79, vcc, 0, v77, vcc
	s_and_b64 vcc, exec, s[6:7]
	global_load_dwordx4 v[80:83], v[76:77], off
	global_load_dwordx4 v[84:87], v[8:9], off
	global_load_dwordx4 v[88:91], v[10:11], off
	global_load_dwordx4 v[92:95], v[8:9], off offset:64
	global_load_dwordx4 v[96:99], v[76:77], off offset:64
	global_load_dwordx4 v[100:103], v[78:79], off
	global_load_dwordx4 v[104:107], v[12:13], off
	global_load_dwordx4 v[108:111], v[78:79], off offset:64
	global_load_dwordx4 v[112:115], v[76:77], off offset:128
	global_load_dwordx4 v[116:119], v[8:9], off offset:128
	global_load_dwordx4 v[120:123], v[14:15], off
	global_load_dwordx4 v[124:127], v[8:9], off offset:192
	global_load_dwordx4 v[132:135], v[76:77], off offset:192
	global_load_dwordx4 v[140:143], v[78:79], off offset:128
	global_load_dwordx4 v[144:147], v[16:17], off
	global_load_dwordx4 v[148:151], v[78:79], off offset:192
	global_load_dwordx4 v[152:155], v[76:77], off offset:256
	global_load_dwordx4 v[156:159], v[8:9], off offset:256
	global_load_dwordx4 v[160:163], v[18:19], off
	global_load_dwordx4 v[164:167], v[8:9], off offset:320
	global_load_dwordx4 v[168:171], v[76:77], off offset:320
	global_load_dwordx4 v[176:179], v[78:79], off offset:256
	global_load_dwordx4 v[180:183], v[20:21], off
	global_load_dwordx4 v[184:187], v[78:79], off offset:320
	global_load_dwordx4 v[188:191], v[76:77], off offset:384
	global_load_dwordx4 v[192:195], v[8:9], off offset:384
	global_load_dwordx4 v[196:199], v[22:23], off
	global_load_dwordx4 v[200:203], v[8:9], off offset:448
	global_load_dwordx4 v[204:207], v[76:77], off offset:448
	global_load_dwordx4 v[208:211], v[78:79], off offset:384
	global_load_dwordx4 v[212:215], v[24:25], off
	global_load_dwordx4 v[216:219], v[78:79], off offset:448
	s_waitcnt vmcnt(30)
	v_mfma_f32_16x16x32_bf16 v[52:55], v[80:83], v[84:87], 0
	s_waitcnt vmcnt(29)
	v_mfma_f32_16x16x32_bf16 v[32:35], v[80:83], v[88:91], 0
	s_waitcnt vmcnt(26)
	v_mfma_f32_16x16x32_bf16 v[36:39], v[100:103], v[84:87], 0
	v_mfma_f32_16x16x32_bf16 v[52:55], v[96:99], v[92:95], v[52:55]
	s_waitcnt vmcnt(25)
	v_mfma_f32_16x16x32_bf16 v[32:35], v[96:99], v[104:107], v[32:35]
	v_mfma_f32_16x16x32_bf16 v[40:43], v[100:103], v[88:91], 0
	s_waitcnt vmcnt(24)
	v_mfma_f32_16x16x32_bf16 v[36:39], v[108:111], v[92:95], v[36:39]
	v_mfma_f32_16x16x32_bf16 v[40:43], v[108:111], v[104:107], v[40:43]
	s_waitcnt vmcnt(22)
	v_mfma_f32_16x16x32_bf16 v[52:55], v[112:115], v[116:119], v[52:55]
	s_waitcnt vmcnt(21)
	v_mfma_f32_16x16x32_bf16 v[32:35], v[112:115], v[120:123], v[32:35]
	s_waitcnt vmcnt(18)
	v_mfma_f32_16x16x32_bf16 v[36:39], v[140:143], v[116:119], v[36:39]
	v_mfma_f32_16x16x32_bf16 v[44:47], v[132:135], v[124:127], v[52:55]
	s_nop 2
	v_mfma_f32_16x16x32_bf16 v[40:43], v[140:143], v[120:123], v[40:43]
	s_waitcnt vmcnt(17)
	v_mfma_f32_16x16x32_bf16 v[32:35], v[132:135], v[144:147], v[32:35]
	s_waitcnt vmcnt(16)
	v_mfma_f32_16x16x32_bf16 v[36:39], v[148:151], v[124:127], v[36:39]
	v_mfma_f32_16x16x32_bf16 v[40:43], v[148:151], v[144:147], v[40:43]
	s_waitcnt vmcnt(14)
	v_mfma_f32_16x16x32_bf16 v[44:47], v[152:155], v[156:159], v[44:47]
	s_waitcnt vmcnt(13)
	v_mfma_f32_16x16x32_bf16 v[32:35], v[152:155], v[160:163], v[32:35]
	s_waitcnt vmcnt(10)
	v_mfma_f32_16x16x32_bf16 v[40:43], v[176:179], v[160:163], v[40:43]
	v_mfma_f32_16x16x32_bf16 v[36:39], v[176:179], v[156:159], v[36:39]
	v_mfma_f32_16x16x32_bf16 v[44:47], v[168:171], v[164:167], v[44:47]
	s_waitcnt vmcnt(9)
	v_mfma_f32_16x16x32_bf16 v[32:35], v[168:171], v[180:183], v[32:35]
	s_waitcnt vmcnt(8)
	v_mfma_f32_16x16x32_bf16 v[36:39], v[184:187], v[164:167], v[36:39]
	v_mfma_f32_16x16x32_bf16 v[40:43], v[184:187], v[180:183], v[40:43]
	s_waitcnt vmcnt(6)
	v_mfma_f32_16x16x32_bf16 v[44:47], v[188:191], v[192:195], v[44:47]
	s_waitcnt vmcnt(5)
	v_mfma_f32_16x16x32_bf16 v[32:35], v[188:191], v[196:199], v[32:35]
	s_barrier
	s_waitcnt vmcnt(2)
	v_mfma_f32_16x16x32_bf16 v[36:39], v[208:211], v[192:195], v[36:39]
	v_mfma_f32_16x16x32_bf16 v[40:43], v[208:211], v[196:199], v[40:43]
	v_mfma_f32_16x16x32_bf16 v[44:47], v[204:207], v[200:203], v[44:47]
	s_waitcnt vmcnt(1)
	v_mfma_f32_16x16x32_bf16 v[32:35], v[204:207], v[212:215], v[32:35]
	s_nop 5
	ds_write_b128 v30, v[44:47]
	s_nop 0
	ds_write_b128 v30, v[32:35] offset:32
	s_waitcnt vmcnt(0)
	v_mfma_f32_16x16x32_bf16 v[36:39], v[216:219], v[200:203], v[36:39]
	v_mfma_f32_16x16x32_bf16 v[32:35], v[216:219], v[212:215], v[40:43]
	s_nop 6
	ds_write_b128 v30, v[36:39] offset:16
	ds_write_b128 v30, v[32:35] offset:48
	s_waitcnt lgkmcnt(0)
	s_barrier
	s_cbranch_vccnz .LBB0_664
	v_lshl_or_b32 v2, s10, 8, v130
	v_or_b32_e32 v2, s11, v2
	v_lshl_add_u64 v[40:41], v[2:3], 2, v[4:5]
	global_load_dwordx4 v[32:35], v[40:41], off
	global_load_dwordx4 v[36:39], v[40:41], off offset:16
	ds_read_b128 v[40:43], v31
	ds_read_b128 v[44:47], v31 offset:16
	ds_read_b128 v[48:51], v31 offset:4096
	ds_read_b128 v[52:55], v31 offset:4112
	ds_read_b128 v[56:59], v31 offset:8192
	ds_read_b128 v[60:63], v31 offset:8208
	ds_read_b128 v[64:67], v31 offset:12288
	ds_read_b128 v[68:71], v31 offset:12304
	ds_read_b128 v[72:75], v31 offset:16384
	ds_read_b128 v[76:79], v31 offset:16400
	ds_read_b128 v[80:83], v31 offset:20480
	ds_read_b128 v[84:87], v31 offset:20496
	ds_read_b128 v[88:91], v31 offset:24576
	ds_read_b128 v[92:95], v31 offset:24592
	ds_read_b128 v[96:99], v31 offset:28672
	ds_read_b128 v[100:103], v31 offset:28688
	s_waitcnt lgkmcnt(14)
	v_pk_add_f32 v[42:43], v[42:43], 0 op_sel_hi:[1,0]
	v_pk_add_f32 v[40:41], v[40:41], 0 op_sel_hi:[1,0]
	v_pk_add_f32 v[46:47], v[46:47], 0 op_sel_hi:[1,0]
	v_pk_add_f32 v[44:45], v[44:45], 0 op_sel_hi:[1,0]
	s_waitcnt lgkmcnt(13)
	v_pk_add_f32 v[42:43], v[42:43], v[50:51]
	v_pk_add_f32 v[40:41], v[40:41], v[48:49]
	s_waitcnt lgkmcnt(12)
	v_pk_add_f32 v[46:47], v[46:47], v[54:55]
	v_pk_add_f32 v[44:45], v[44:45], v[52:53]
	s_waitcnt lgkmcnt(11)
	v_pk_add_f32 v[42:43], v[42:43], v[58:59]
	v_pk_add_f32 v[40:41], v[40:41], v[56:57]
	s_waitcnt lgkmcnt(10)
	v_pk_add_f32 v[46:47], v[46:47], v[62:63]
	v_pk_add_f32 v[44:45], v[44:45], v[60:61]
	s_waitcnt lgkmcnt(9)
	v_pk_add_f32 v[42:43], v[42:43], v[66:67]
	v_pk_add_f32 v[40:41], v[40:41], v[64:65]
	s_waitcnt lgkmcnt(8)
	v_pk_add_f32 v[46:47], v[46:47], v[70:71]
	v_pk_add_f32 v[44:45], v[44:45], v[68:69]
	s_waitcnt lgkmcnt(7)
	v_pk_add_f32 v[42:43], v[42:43], v[74:75]
	v_pk_add_f32 v[40:41], v[40:41], v[72:73]
	s_waitcnt lgkmcnt(6)
	v_pk_add_f32 v[46:47], v[46:47], v[78:79]
	v_pk_add_f32 v[44:45], v[44:45], v[76:77]
	s_waitcnt lgkmcnt(5)
	v_pk_add_f32 v[42:43], v[42:43], v[82:83]
	v_pk_add_f32 v[40:41], v[40:41], v[80:81]
	s_waitcnt lgkmcnt(4)
	v_pk_add_f32 v[46:47], v[46:47], v[86:87]
	v_pk_add_f32 v[44:45], v[44:45], v[84:85]
	s_waitcnt lgkmcnt(3)
	v_pk_add_f32 v[42:43], v[42:43], v[90:91]
	v_pk_add_f32 v[40:41], v[40:41], v[88:89]
	s_waitcnt lgkmcnt(2)
	v_pk_add_f32 v[46:47], v[46:47], v[94:95]
	v_pk_add_f32 v[44:45], v[44:45], v[92:93]
	s_waitcnt lgkmcnt(1)
	v_pk_add_f32 v[42:43], v[42:43], v[98:99]
	v_pk_add_f32 v[40:41], v[40:41], v[96:97]
	s_waitcnt lgkmcnt(0)
	v_pk_add_f32 v[46:47], v[46:47], v[102:103]
	v_pk_add_f32 v[44:45], v[44:45], v[100:101]
	v_lshlrev_b32_e32 v2, 1, v2
	s_waitcnt vmcnt(1)
	v_pk_add_f32 v[34:35], v[42:43], v[34:35]
	v_pk_add_f32 v[32:33], v[40:41], v[32:33]
	s_waitcnt vmcnt(0)
	v_pk_add_f32 v[38:39], v[46:47], v[38:39]
	v_pk_add_f32 v[36:37], v[44:45], v[36:37]
	v_cvt_pk_bf16_f32 v32, v32, v33
	v_cvt_pk_bf16_f32 v33, v34, v35
	v_cvt_pk_bf16_f32 v34, v36, v37
	v_cvt_pk_bf16_f32 v35, v38, v39
	v_lshl_add_u64 v[36:37], v[6:7], 0, v[2:3]
	global_store_dwordx4 v[36:37], v[32:35], off
	s_branch .LBB0_664

.LBB0_750:
	s_lshr_b32 s10, s3, 3
	s_and_b32 s11, s1, 0xe0
	s_lshl_b32 s12, s10, 20
	s_add_u32 s12, s34, s12
	s_addc_u32 s13, s35, 0
	s_lshl_b32 s14, s11, 12
	s_add_u32 s12, s12, s14
	s_addc_u32 s13, s13, 0
	s_add_u32 s12, s12, s4
	s_addc_u32 s13, s13, s5
	v_lshl_add_u64 v[34:35], s[12:13], 0, v[28:29]
	v_lshl_add_u64 v[78:79], v[34:35], 0, v[30:31]
	v_add_co_u32_e32 v80, vcc, s0, v78
	s_nop 1
	v_addc_co_u32_e32 v81, vcc, 0, v79, vcc
	s_and_b64 vcc, exec, s[6:7]
	global_load_dwordx4 v[84:87], v[78:79], off
	global_load_dwordx4 v[88:91], v[4:5], off
	global_load_dwordx4 v[92:95], v[6:7], off
	global_load_dwordx4 v[96:99], v[4:5], off offset:64
	global_load_dwordx4 v[100:103], v[78:79], off offset:64
	global_load_dwordx4 v[104:107], v[80:81], off
	global_load_dwordx4 v[108:111], v[8:9], off
	global_load_dwordx4 v[112:115], v[80:81], off offset:64
	global_load_dwordx4 v[116:119], v[78:79], off offset:128
	global_load_dwordx4 v[120:123], v[4:5], off offset:128
	global_load_dwordx4 v[124:127], v[10:11], off
	global_load_dwordx4 v[132:135], v[4:5], off offset:192
	global_load_dwordx4 v[140:143], v[78:79], off offset:192
	global_load_dwordx4 v[144:147], v[80:81], off offset:128
	global_load_dwordx4 v[148:151], v[12:13], off
	global_load_dwordx4 v[152:155], v[80:81], off offset:192
	global_load_dwordx4 v[156:159], v[78:79], off offset:256
	global_load_dwordx4 v[160:163], v[4:5], off offset:256
	global_load_dwordx4 v[164:167], v[14:15], off
	global_load_dwordx4 v[168:171], v[4:5], off offset:320
	global_load_dwordx4 v[176:179], v[78:79], off offset:320
	global_load_dwordx4 v[180:183], v[80:81], off offset:256
	global_load_dwordx4 v[184:187], v[16:17], off
	global_load_dwordx4 v[188:191], v[80:81], off offset:320
	global_load_dwordx4 v[192:195], v[78:79], off offset:384
	global_load_dwordx4 v[196:199], v[4:5], off offset:384
	global_load_dwordx4 v[200:203], v[18:19], off
	global_load_dwordx4 v[204:207], v[4:5], off offset:448
	global_load_dwordx4 v[208:211], v[78:79], off offset:448
	global_load_dwordx4 v[212:215], v[80:81], off offset:384
	global_load_dwordx4 v[216:219], v[20:21], off
	global_load_dwordx4 v[220:223], v[80:81], off offset:448
	s_waitcnt vmcnt(30)
	v_mfma_f32_16x16x32_bf16 v[54:57], v[84:87], v[88:91], 0
	s_waitcnt vmcnt(29)
	v_mfma_f32_16x16x32_bf16 v[34:37], v[84:87], v[92:95], 0
	s_waitcnt vmcnt(26)
	v_mfma_f32_16x16x32_bf16 v[38:41], v[104:107], v[88:91], 0
	v_mfma_f32_16x16x32_bf16 v[54:57], v[100:103], v[96:99], v[54:57]
	s_waitcnt vmcnt(25)
	v_mfma_f32_16x16x32_bf16 v[34:37], v[100:103], v[108:111], v[34:37]
	v_mfma_f32_16x16x32_bf16 v[42:45], v[104:107], v[92:95], 0
	s_waitcnt vmcnt(24)
	v_mfma_f32_16x16x32_bf16 v[38:41], v[112:115], v[96:99], v[38:41]
	v_mfma_f32_16x16x32_bf16 v[42:45], v[112:115], v[108:111], v[42:45]
	s_waitcnt vmcnt(22)
	v_mfma_f32_16x16x32_bf16 v[54:57], v[116:119], v[120:123], v[54:57]
	s_waitcnt vmcnt(21)
	v_mfma_f32_16x16x32_bf16 v[34:37], v[116:119], v[124:127], v[34:37]
	s_waitcnt vmcnt(18)
	v_mfma_f32_16x16x32_bf16 v[38:41], v[144:147], v[120:123], v[38:41]
	v_mfma_f32_16x16x32_bf16 v[46:49], v[140:143], v[132:135], v[54:57]
	s_nop 2
	v_mfma_f32_16x16x32_bf16 v[42:45], v[144:147], v[124:127], v[42:45]
	s_waitcnt vmcnt(17)
	v_mfma_f32_16x16x32_bf16 v[34:37], v[140:143], v[148:151], v[34:37]
	s_waitcnt vmcnt(16)
	v_mfma_f32_16x16x32_bf16 v[38:41], v[152:155], v[132:135], v[38:41]
	v_mfma_f32_16x16x32_bf16 v[42:45], v[152:155], v[148:151], v[42:45]
	s_waitcnt vmcnt(14)
	v_mfma_f32_16x16x32_bf16 v[46:49], v[156:159], v[160:163], v[46:49]
	s_waitcnt vmcnt(13)
	v_mfma_f32_16x16x32_bf16 v[34:37], v[156:159], v[164:167], v[34:37]
	s_waitcnt vmcnt(10)
	v_mfma_f32_16x16x32_bf16 v[42:45], v[180:183], v[164:167], v[42:45]
	v_mfma_f32_16x16x32_bf16 v[38:41], v[180:183], v[160:163], v[38:41]
	v_mfma_f32_16x16x32_bf16 v[46:49], v[176:179], v[168:171], v[46:49]
	s_waitcnt vmcnt(9)
	v_mfma_f32_16x16x32_bf16 v[34:37], v[176:179], v[184:187], v[34:37]
	s_waitcnt vmcnt(8)
	v_mfma_f32_16x16x32_bf16 v[38:41], v[188:191], v[168:171], v[38:41]
	v_mfma_f32_16x16x32_bf16 v[42:45], v[188:191], v[184:187], v[42:45]
	s_waitcnt vmcnt(6)
	v_mfma_f32_16x16x32_bf16 v[46:49], v[192:195], v[196:199], v[46:49]
	s_waitcnt vmcnt(5)
	v_mfma_f32_16x16x32_bf16 v[34:37], v[192:195], v[200:203], v[34:37]
	s_barrier
	s_waitcnt vmcnt(2)
	v_mfma_f32_16x16x32_bf16 v[38:41], v[212:215], v[196:199], v[38:41]
	v_mfma_f32_16x16x32_bf16 v[42:45], v[212:215], v[200:203], v[42:45]
	v_mfma_f32_16x16x32_bf16 v[46:49], v[208:211], v[204:207], v[46:49]
	s_waitcnt vmcnt(1)
	v_mfma_f32_16x16x32_bf16 v[34:37], v[208:211], v[216:219], v[34:37]
	s_nop 5
	ds_write_b128 v32, v[46:49]
	s_nop 0
	ds_write_b128 v32, v[34:37] offset:32
	s_waitcnt vmcnt(0)
	v_mfma_f32_16x16x32_bf16 v[38:41], v[220:223], v[204:207], v[38:41]
	v_mfma_f32_16x16x32_bf16 v[34:37], v[220:223], v[216:219], v[42:45]
	s_nop 6
	ds_write_b128 v32, v[38:41] offset:16
	ds_write_b128 v32, v[34:37] offset:48
	s_waitcnt lgkmcnt(0)
	s_barrier
	s_cbranch_vccnz .LBB0_749
	ds_read_b128 v[34:37], v33
	ds_read_b128 v[38:41], v33 offset:16
	v_lshl_or_b32 v2, s10, 8, v130
	v_or_b32_e32 v2, s11, v2
	v_lshlrev_b32_e32 v2, 1, v2
	s_waitcnt lgkmcnt(1)
	v_pk_add_f32 v[54:55], v[36:37], 0 op_sel_hi:[1,0]
	v_lshl_add_u64 v[36:37], v[22:23], 0, v[2:3]
	global_load_dwordx4 v[42:45], v[36:37], off
	v_lshl_add_u64 v[36:37], v[24:25], 0, v[2:3]
	global_load_dwordx4 v[46:49], v[36:37], off
	ds_read_b128 v[50:53], v33 offset:4096
	v_pk_add_f32 v[56:57], v[34:35], 0 op_sel_hi:[1,0]
	ds_read_b128 v[34:37], v33 offset:4112
	s_waitcnt lgkmcnt(2)
	v_pk_add_f32 v[58:59], v[40:41], 0 op_sel_hi:[1,0]
	v_pk_add_f32 v[60:61], v[38:39], 0 op_sel_hi:[1,0]
	ds_read_b128 v[38:41], v33 offset:8192
	s_waitcnt lgkmcnt(2)
	v_pk_add_f32 v[54:55], v[54:55], v[52:53]
	v_pk_add_f32 v[56:57], v[56:57], v[50:51]
	s_waitcnt lgkmcnt(1)
	v_pk_add_f32 v[58:59], v[58:59], v[36:37]
	ds_read_b128 v[50:53], v33 offset:8208
	v_pk_add_f32 v[60:61], v[60:61], v[34:35]
	ds_read_b128 v[34:37], v33 offset:12288
	s_waitcnt lgkmcnt(2)
	v_pk_add_f32 v[54:55], v[54:55], v[40:41]
	v_pk_add_f32 v[56:57], v[56:57], v[38:39]
	ds_read_b128 v[38:41], v33 offset:12304
	s_waitcnt lgkmcnt(2)
	v_pk_add_f32 v[58:59], v[58:59], v[52:53]
	v_pk_add_f32 v[60:61], v[60:61], v[50:51]
	s_waitcnt lgkmcnt(1)
	v_pk_add_f32 v[54:55], v[54:55], v[36:37]
	ds_read_b128 v[50:53], v33 offset:16384
	v_pk_add_f32 v[56:57], v[56:57], v[34:35]
	ds_read_b128 v[34:37], v33 offset:16400
	s_waitcnt lgkmcnt(2)
	v_pk_add_f32 v[58:59], v[58:59], v[40:41]
	v_pk_add_f32 v[60:61], v[60:61], v[38:39]
	ds_read_b128 v[38:41], v33 offset:20480
	s_waitcnt lgkmcnt(2)
	v_pk_add_f32 v[54:55], v[54:55], v[52:53]
	v_pk_add_f32 v[56:57], v[56:57], v[50:51]
	s_waitcnt lgkmcnt(1)
	v_pk_add_f32 v[58:59], v[58:59], v[36:37]
	ds_read_b128 v[50:53], v33 offset:20496
	v_pk_add_f32 v[60:61], v[60:61], v[34:35]
	ds_read_b128 v[34:37], v33 offset:24576
	s_waitcnt lgkmcnt(2)
	v_pk_add_f32 v[54:55], v[54:55], v[40:41]
	v_pk_add_f32 v[56:57], v[56:57], v[38:39]
	ds_read_b128 v[38:41], v33 offset:24592
	s_waitcnt lgkmcnt(2)
	v_pk_add_f32 v[58:59], v[58:59], v[52:53]
	v_pk_add_f32 v[60:61], v[60:61], v[50:51]
	s_waitcnt lgkmcnt(1)
	v_pk_add_f32 v[54:55], v[54:55], v[36:37]
	ds_read_b128 v[50:53], v33 offset:28672
	v_pk_add_f32 v[56:57], v[56:57], v[34:35]
	ds_read_b128 v[34:37], v33 offset:28688
	s_waitcnt lgkmcnt(2)
	v_pk_add_f32 v[38:39], v[60:61], v[38:39]
	v_pk_add_f32 v[40:41], v[58:59], v[40:41]
	s_waitcnt lgkmcnt(1)
	v_pk_add_f32 v[50:51], v[56:57], v[50:51]
	v_pk_add_f32 v[52:53], v[54:55], v[52:53]
	s_waitcnt lgkmcnt(0)
	v_pk_add_f32 v[34:35], v[38:39], v[34:35]
	v_mul_f32_e32 v38, 0xbfb8aa3b, v50
	v_mul_f32_e32 v34, 0xbfb8aa3b, v34
	v_exp_f32_e32 v38, v38
	v_exp_f32_e32 v39, v34
	v_mul_f32_e32 v35, 0xbfb8aa3b, v35
	v_pk_add_f32 v[36:37], v[40:41], v[36:37]
	v_add_f32_e32 v34, 1.0, v38
	v_add_f32_e32 v38, 1.0, v39
	v_mul_f32_e32 v39, 0xbfb8aa3b, v51
	v_exp_f32_e32 v39, v39
	v_exp_f32_e32 v40, v35
	v_mul_f32_e32 v36, 0xbfb8aa3b, v36
	v_exp_f32_e32 v41, v36
	v_add_f32_e32 v35, 1.0, v39
	v_add_f32_e32 v39, 1.0, v40
	v_mul_f32_e32 v40, 0xbfb8aa3b, v52
	v_exp_f32_e32 v40, v40
	v_mul_f32_e32 v37, 0xbfb8aa3b, v37
	v_exp_f32_e32 v50, v37
	v_rcp_f32_e32 v38, v38
	v_add_f32_e32 v36, 1.0, v40
	v_add_f32_e32 v40, 1.0, v41
	v_mul_f32_e32 v41, 0xbfb8aa3b, v53
	v_exp_f32_e32 v41, v41
	v_rcp_f32_e32 v36, v36
	v_rcp_f32_e32 v39, v39
	v_rcp_f32_e32 v34, v34
	v_add_f32_e32 v37, 1.0, v41
	v_rcp_f32_e32 v37, v37
	v_add_f32_e32 v41, 1.0, v50
	v_rcp_f32_e32 v35, v35
	v_rcp_f32_e32 v40, v40
	v_rcp_f32_e32 v41, v41
	s_waitcnt vmcnt(1)
	v_lshlrev_b32_e32 v50, 16, v42
	v_and_b32_e32 v51, 0xffff0000, v42
	s_waitcnt vmcnt(0)
	v_lshlrev_b32_e32 v52, 16, v46
	v_and_b32_e32 v53, 0xffff0000, v46
	v_lshlrev_b32_e32 v42, 16, v43
	v_and_b32_e32 v43, 0xffff0000, v43
	v_lshlrev_b32_e32 v46, 16, v47
	v_and_b32_e32 v47, 0xffff0000, v47
	v_pk_fma_f32 v[36:37], v[36:37], v[42:43], v[46:47]
	v_lshlrev_b32_e32 v42, 16, v44
	v_and_b32_e32 v43, 0xffff0000, v44
	v_lshlrev_b32_e32 v46, 16, v48
	v_and_b32_e32 v47, 0xffff0000, v48
	v_pk_fma_f32 v[38:39], v[38:39], v[42:43], v[46:47]
	v_lshlrev_b32_e32 v42, 16, v45
	v_and_b32_e32 v43, 0xffff0000, v45
	v_lshlrev_b32_e32 v44, 16, v49
	v_and_b32_e32 v45, 0xffff0000, v49
	v_pk_fma_f32 v[34:35], v[34:35], v[50:51], v[52:53]
	v_pk_fma_f32 v[40:41], v[40:41], v[42:43], v[44:45]
	v_cvt_pk_bf16_f32 v34, v34, v35
	v_cvt_pk_bf16_f32 v35, v36, v37
	v_cvt_pk_bf16_f32 v36, v38, v39
	v_cvt_pk_bf16_f32 v37, v40, v41
	v_lshl_add_u64 v[38:39], v[26:27], 0, v[2:3]
	global_store_dwordx4 v[38:39], v[34:37], off
	s_branch .LBB0_749

.LBB0_961:
	v_readlane_b32 s16, v244, 5
	v_readlane_b32 s17, v244, 6
	s_add_u32 s0, s16, s0
	s_addc_u32 s1, s17, s1
	s_add_u32 s0, s0, s8
	s_addc_u32 s1, s1, s9
	s_and_b32 s16, s24, 0xe0
	s_lshl_b32 s4, s16, 12
	s_add_u32 s2, s2, s4
	s_addc_u32 s3, s3, 0
	s_add_u32 s2, s2, s8
	s_addc_u32 s3, s3, s9
	v_lshl_add_u64 v[2:3], s[2:3], 0, v[26:27]
	v_lshl_add_u64 v[62:63], v[2:3], 0, v[28:29]
	v_lshl_add_u64 v[2:3], s[0:1], 0, v[30:31]
	v_lshl_add_u64 v[14:15], v[2:3], 0, v[28:29]
	v_add_co_u32_e32 v6, vcc, s27, v14
	s_nop 1
	v_addc_co_u32_e32 v7, vcc, 0, v15, vcc
	v_add_co_u32_e32 v64, vcc, s28, v14
	s_nop 1
	v_addc_co_u32_e32 v65, vcc, 0, v15, vcc
	v_add_co_u32_e32 v68, vcc, s23, v62
	s_nop 1
	v_addc_co_u32_e32 v69, vcc, 0, v63, vcc
	v_lshl_add_u64 v[66:67], v[14:15], 0, s[12:13]
	s_andn2_b64 vcc, exec, s[6:7]
	global_load_dwordx4 v[72:75], v[62:63], off
	global_load_dwordx4 v[80:83], v[6:7], off
	global_load_dwordx4 v[84:87], v[64:65], off
	global_load_dwordx4 v[88:91], v[64:65], off offset:64
	global_load_dwordx4 v[92:95], v[66:67], off offset:448
	global_load_dwordx4 v[96:99], v[62:63], off offset:64
	global_load_dwordx4 v[100:103], v[68:69], off
	global_load_dwordx4 v[104:107], v[68:69], off offset:64
	global_load_dwordx4 v[108:111], v[66:67], off offset:64
	global_load_dwordx4 v[112:115], v[66:67], off offset:128
	global_load_dwordx4 v[116:119], v[62:63], off offset:128
	global_load_dwordx4 v[120:123], v[62:63], off offset:192
	global_load_dwordx4 v[124:127], v[64:65], off offset:128
	global_load_dwordx4 v[140:143], v[64:65], off offset:192
	global_load_dwordx4 v[148:151], v[68:69], off offset:128
	global_load_dwordx4 v[152:155], v[68:69], off offset:192
	global_load_dwordx4 v[156:159], v[66:67], off offset:192
	global_load_dwordx4 v[160:163], v[66:67], off offset:256
	global_load_dwordx4 v[164:167], v[62:63], off offset:256
	global_load_dwordx4 v[168:171], v[62:63], off offset:320
	global_load_dwordx4 v[180:183], v[64:65], off offset:256
	global_load_dwordx4 v[184:187], v[64:65], off offset:320
	global_load_dwordx4 v[188:191], v[68:69], off offset:256
	global_load_dwordx4 v[192:195], v[68:69], off offset:320
	global_load_dwordx4 v[196:199], v[66:67], off offset:320
	global_load_dwordx4 v[200:203], v[66:67], off offset:384
	global_load_dwordx4 v[204:207], v[62:63], off offset:384
	global_load_dwordx4 v[208:211], v[64:65], off offset:384
	global_load_dwordx4 v[212:215], v[62:63], off offset:448
	global_load_dwordx4 v[216:219], v[68:69], off offset:384
	global_load_dwordx4 v[220:223], v[64:65], off offset:448
	global_load_dwordx4 v[224:227], v[68:69], off offset:448
	s_nop 0
	s_nop 0
	s_nop 0
	s_waitcnt vmcnt(30)
	v_mfma_f32_16x16x32_bf16 v[42:45], v[72:75], v[80:83], 0
	s_waitcnt vmcnt(29)
	v_mfma_f32_16x16x32_bf16 v[2:5], v[72:75], v[84:87], 0
	s_waitcnt vmcnt(25)
	v_mfma_f32_16x16x32_bf16 v[6:9], v[100:103], v[80:83], 0
	v_mfma_f32_16x16x32_bf16 v[10:13], v[100:103], v[84:87], 0
	v_mfma_f32_16x16x32_bf16 v[2:5], v[96:99], v[88:91], v[2:5]
	s_waitcnt vmcnt(24)
	v_mfma_f32_16x16x32_bf16 v[10:13], v[104:107], v[88:91], v[10:13]
	s_waitcnt vmcnt(23)
	v_mfma_f32_16x16x32_bf16 v[42:45], v[96:99], v[108:111], v[42:45]
	v_mfma_f32_16x16x32_bf16 v[6:9], v[104:107], v[108:111], v[6:9]
	s_waitcnt vmcnt(21)
	v_mfma_f32_16x16x32_bf16 v[42:45], v[116:119], v[112:115], v[42:45]
	s_waitcnt vmcnt(19)
	v_mfma_f32_16x16x32_bf16 v[2:5], v[116:119], v[124:127], v[2:5]
	s_waitcnt vmcnt(18)
	v_mfma_f32_16x16x32_bf16 v[2:5], v[120:123], v[140:143], v[2:5]
	s_waitcnt vmcnt(17)
	v_mfma_f32_16x16x32_bf16 v[6:9], v[148:151], v[112:115], v[6:9]
	v_mfma_f32_16x16x32_bf16 v[10:13], v[148:151], v[124:127], v[10:13]
	s_waitcnt vmcnt(16)
	v_mfma_f32_16x16x32_bf16 v[10:13], v[152:155], v[140:143], v[10:13]
	s_waitcnt vmcnt(15)
	v_mfma_f32_16x16x32_bf16 v[42:45], v[120:123], v[156:159], v[42:45]
	v_mfma_f32_16x16x32_bf16 v[6:9], v[152:155], v[156:159], v[6:9]
	s_waitcnt vmcnt(13)
	v_mfma_f32_16x16x32_bf16 v[42:45], v[164:167], v[160:163], v[42:45]
	s_waitcnt vmcnt(11)
	v_mfma_f32_16x16x32_bf16 v[2:5], v[164:167], v[180:183], v[2:5]
	s_waitcnt vmcnt(10)
	v_mfma_f32_16x16x32_bf16 v[2:5], v[168:171], v[184:187], v[2:5]
	s_waitcnt vmcnt(9)
	v_mfma_f32_16x16x32_bf16 v[6:9], v[188:191], v[160:163], v[6:9]
	v_mfma_f32_16x16x32_bf16 v[10:13], v[188:191], v[180:183], v[10:13]
	s_waitcnt vmcnt(8)
	v_mfma_f32_16x16x32_bf16 v[10:13], v[192:195], v[184:187], v[10:13]
	s_waitcnt vmcnt(7)
	v_mfma_f32_16x16x32_bf16 v[42:45], v[168:171], v[196:199], v[42:45]
	v_mfma_f32_16x16x32_bf16 v[6:9], v[192:195], v[196:199], v[6:9]
	s_waitcnt vmcnt(2)
	v_mfma_f32_16x16x32_bf16 v[6:9], v[216:219], v[200:203], v[6:9]
	v_mfma_f32_16x16x32_bf16 v[42:45], v[204:207], v[200:203], v[42:45]
	v_mfma_f32_16x16x32_bf16 v[2:5], v[204:207], v[208:211], v[2:5]
	s_barrier
	v_mfma_f32_16x16x32_bf16 v[10:13], v[216:219], v[208:211], v[10:13]
	v_mfma_f32_16x16x32_bf16 v[38:41], v[212:215], v[92:95], v[42:45]
	s_waitcnt vmcnt(1)
	v_mfma_f32_16x16x32_bf16 v[2:5], v[212:215], v[220:223], v[2:5]
	s_waitcnt vmcnt(0)
	v_mfma_f32_16x16x32_bf16 v[6:9], v[224:227], v[92:95], v[6:9]
	v_mfma_f32_16x16x32_bf16 v[10:13], v[224:227], v[220:223], v[10:13]
	s_nop 2
	ds_write_b128 v32, v[38:41]
	s_nop 0
	ds_write_b128 v32, v[2:5] offset:32
	s_nop 0
	ds_write_b128 v32, v[6:9] offset:16
	ds_write_b128 v32, v[10:13] offset:48
	s_waitcnt lgkmcnt(0)
	s_barrier
	s_cbranch_vccnz .LBB0_946
	ds_read_b128 v[2:5], v33
	ds_read_b128 v[6:9], v33 offset:16
	ds_read_b128 v[10:13], v33 offset:4096
	s_lshl_b32 s0, s31, 8
	s_and_b32 s17, s0, 0x700
	s_waitcnt lgkmcnt(2)
	v_pk_add_f32 v[14:15], v[4:5], 0 op_sel_hi:[1,0]
	v_pk_add_f32 v[16:17], v[2:3], 0 op_sel_hi:[1,0]
	ds_read_b128 v[2:5], v33 offset:4112
	s_waitcnt lgkmcnt(2)
	v_pk_add_f32 v[34:35], v[8:9], 0 op_sel_hi:[1,0]
	v_pk_add_f32 v[36:37], v[6:7], 0 op_sel_hi:[1,0]
	ds_read_b128 v[6:9], v33 offset:8192
	s_waitcnt lgkmcnt(2)
	v_pk_add_f32 v[14:15], v[14:15], v[12:13]
	v_pk_add_f32 v[16:17], v[16:17], v[10:11]
	s_waitcnt lgkmcnt(1)
	v_pk_add_f32 v[34:35], v[34:35], v[4:5]
	ds_read_b128 v[10:13], v33 offset:8208
	v_pk_add_f32 v[36:37], v[36:37], v[2:3]
	ds_read_b128 v[2:5], v33 offset:12288
	s_waitcnt lgkmcnt(2)
	v_pk_add_f32 v[14:15], v[14:15], v[8:9]
	v_pk_add_f32 v[16:17], v[16:17], v[6:7]
	ds_read_b128 v[6:9], v33 offset:12304
	s_waitcnt lgkmcnt(2)
	v_pk_add_f32 v[34:35], v[34:35], v[12:13]
	v_pk_add_f32 v[36:37], v[36:37], v[10:11]
	s_waitcnt lgkmcnt(1)
	v_pk_add_f32 v[14:15], v[14:15], v[4:5]
	ds_read_b128 v[10:13], v33 offset:16384
	v_pk_add_f32 v[16:17], v[16:17], v[2:3]
	ds_read_b128 v[2:5], v33 offset:16400
	s_waitcnt lgkmcnt(2)
	v_pk_add_f32 v[34:35], v[34:35], v[8:9]
	v_pk_add_f32 v[36:37], v[36:37], v[6:7]
	ds_read_b128 v[6:9], v33 offset:20480
	s_waitcnt lgkmcnt(2)
	v_pk_add_f32 v[14:15], v[14:15], v[12:13]
	v_pk_add_f32 v[16:17], v[16:17], v[10:11]
	s_waitcnt lgkmcnt(1)
	v_pk_add_f32 v[34:35], v[34:35], v[4:5]
	ds_read_b128 v[10:13], v33 offset:20496
	v_pk_add_f32 v[36:37], v[36:37], v[2:3]
	ds_read_b128 v[2:5], v33 offset:24576
	s_waitcnt lgkmcnt(2)
	v_pk_add_f32 v[14:15], v[14:15], v[8:9]
	v_pk_add_f32 v[16:17], v[16:17], v[6:7]
	ds_read_b128 v[6:9], v33 offset:24592
	s_waitcnt lgkmcnt(2)
	v_pk_add_f32 v[34:35], v[34:35], v[12:13]
	v_pk_add_f32 v[36:37], v[36:37], v[10:11]
	s_waitcnt lgkmcnt(1)
	v_pk_add_f32 v[4:5], v[14:15], v[4:5]
	ds_read_b128 v[10:13], v33 offset:28672
	v_pk_add_f32 v[2:3], v[16:17], v[2:3]
	ds_read_b128 v[14:17], v33 offset:28688
	s_waitcnt lgkmcnt(2)
	v_pk_add_f32 v[8:9], v[34:35], v[8:9]
	v_pk_add_f32 v[6:7], v[36:37], v[6:7]
	s_waitcnt lgkmcnt(1)
	v_pk_add_f32 v[4:5], v[4:5], v[12:13]
	v_pk_add_f32 v[2:3], v[2:3], v[10:11]
	s_waitcnt lgkmcnt(0)
	v_pk_add_f32 v[8:9], v[8:9], v[16:17]
	s_cmpk_gt_u32 s29, 0xbf
	v_pk_add_f32 v[6:7], v[6:7], v[14:15]
	s_cbranch_scc0 .LBB0_969
	s_xor_b64 s[0:1], s[14:15], -1
	s_and_b64 vcc, exec, s[0:1]
	s_cbranch_vccz .LBB0_970
	s_mov_b64 s[0:1], 0
	s_cmpk_lt_u32 s16, 0x80
	s_mov_b64 s[2:3], 0
	s_cbranch_scc0 .LBB0_971
	v_mov_b64_e32 v[16:17], v[8:9]
	v_mov_b64_e32 v[12:13], v[4:5]
	s_mov_b64 s[2:3], 0x80
	s_cmp_lg_u32 s31, 32
	v_mov_b64_e32 v[14:15], v[6:7]
	v_mov_b64_e32 v[10:11], v[2:3]
	s_cbranch_scc1 .LBB0_967
	v_add_f32_e32 v11, v6, v6
	v_mul_f32_e32 v11, 0xbfb8aa3b, v11
	v_add_f32_e32 v12, v3, v3
	v_exp_f32_e32 v11, v11
	v_mul_f32_e32 v12, 0xbfb8aa3b, v12
	v_exp_f32_e32 v12, v12
	v_add_f32_e32 v13, v4, v4
	v_add_f32_e32 v11, 1.0, v11
	v_rcp_f32_e32 v14, v11
	v_add_f32_e32 v11, 1.0, v12
	v_add_f32_e32 v12, v7, v7
	v_add_f32_e32 v15, v8, v8
	v_mul_f32_e32 v12, 0xbfb8aa3b, v12
	v_mul_f32_e32 v13, 0xbfb8aa3b, v13
	v_mul_f32_e32 v15, 0xbfb8aa3b, v15
	v_exp_f32_e32 v12, v12
	v_exp_f32_e32 v13, v13
	v_exp_f32_e32 v15, v15
	v_add_f32_e32 v10, v2, v2
	v_add_f32_e32 v18, 1.0, v12
	v_add_f32_e32 v12, 1.0, v13
	v_add_f32_e32 v13, 1.0, v15
	v_add_f32_e32 v15, v5, v5
	v_add_f32_e32 v16, v9, v9
	v_mul_f32_e32 v10, 0xbfb8aa3b, v10
	v_mul_f32_e32 v15, 0xbfb8aa3b, v15
	v_mul_f32_e32 v16, 0xbfb8aa3b, v16
	v_exp_f32_e32 v10, v10
	v_exp_f32_e32 v15, v15
	v_exp_f32_e32 v17, v16
	v_rcp_f32_e32 v16, v13
	v_add_f32_e32 v10, 1.0, v10
	v_add_f32_e32 v13, 1.0, v15
	v_add_f32_e32 v15, 1.0, v17
	v_rcp_f32_e32 v10, v10
	v_rcp_f32_e32 v11, v11
	v_rcp_f32_e32 v12, v12
	v_rcp_f32_e32 v13, v13
	v_rcp_f32_e32 v17, v15
	v_rcp_f32_e32 v15, v18
	v_pk_fma_f32 v[10:11], v[10:11], 2.0, -1.0 op_sel_hi:[1,0,0]
	v_pk_fma_f32 v[12:13], v[12:13], 2.0, -1.0 op_sel_hi:[1,0,0]
	v_pk_fma_f32 v[16:17], v[16:17], 2.0, -1.0 op_sel_hi:[1,0,0]
	v_pk_fma_f32 v[14:15], v[14:15], 2.0, -1.0 op_sel_hi:[1,0,0]
	s_mov_b64 s[2:3], 0

.LBB0_1271:
	s_lshr_b32 s10, s9, 3
	s_and_b32 s11, s3, 0xe0
	s_lshl_b32 s12, s10, 20
	s_add_u32 s12, s30, s12
	s_addc_u32 s13, s31, 0
	s_lshl_b32 s14, s11, 12
	s_add_u32 s12, s12, s14
	s_addc_u32 s13, s13, 0
	s_add_u32 s12, s12, s0
	s_addc_u32 s13, s13, s1
	v_lshl_add_u64 v[32:33], s[12:13], 0, v[26:27]
	v_lshl_add_u64 v[76:77], v[32:33], 0, v[28:29]
	v_add_co_u32_e32 v78, vcc, s2, v76
	s_nop 1
	v_addc_co_u32_e32 v79, vcc, 0, v77, vcc
	s_and_b64 vcc, exec, s[6:7]
	global_load_dwordx4 v[80:83], v[76:77], off
	global_load_dwordx4 v[84:87], v[8:9], off
	global_load_dwordx4 v[88:91], v[10:11], off
	global_load_dwordx4 v[92:95], v[8:9], off offset:64
	global_load_dwordx4 v[96:99], v[76:77], off offset:64
	global_load_dwordx4 v[100:103], v[78:79], off
	global_load_dwordx4 v[104:107], v[12:13], off
	global_load_dwordx4 v[108:111], v[78:79], off offset:64
	global_load_dwordx4 v[112:115], v[76:77], off offset:128
	global_load_dwordx4 v[116:119], v[8:9], off offset:128
	global_load_dwordx4 v[120:123], v[14:15], off
	global_load_dwordx4 v[124:127], v[8:9], off offset:192
	global_load_dwordx4 v[128:131], v[76:77], off offset:192
	global_load_dwordx4 v[132:135], v[78:79], off offset:128
	global_load_dwordx4 v[144:147], v[16:17], off
	global_load_dwordx4 v[148:151], v[78:79], off offset:192
	global_load_dwordx4 v[152:155], v[76:77], off offset:256
	global_load_dwordx4 v[156:159], v[8:9], off offset:256
	global_load_dwordx4 v[160:163], v[18:19], off
	global_load_dwordx4 v[164:167], v[8:9], off offset:320
	global_load_dwordx4 v[168:171], v[76:77], off offset:320
	global_load_dwordx4 v[176:179], v[78:79], off offset:256
	global_load_dwordx4 v[180:183], v[20:21], off
	global_load_dwordx4 v[184:187], v[78:79], off offset:320
	global_load_dwordx4 v[188:191], v[76:77], off offset:384
	global_load_dwordx4 v[192:195], v[8:9], off offset:384
	global_load_dwordx4 v[196:199], v[22:23], off
	global_load_dwordx4 v[200:203], v[8:9], off offset:448
	global_load_dwordx4 v[204:207], v[76:77], off offset:448
	global_load_dwordx4 v[208:211], v[78:79], off offset:384
	global_load_dwordx4 v[212:215], v[24:25], off
	global_load_dwordx4 v[216:219], v[78:79], off offset:448
	s_waitcnt vmcnt(30)
	v_mfma_f32_16x16x32_bf16 v[52:55], v[80:83], v[84:87], 0
	s_waitcnt vmcnt(29)
	v_mfma_f32_16x16x32_bf16 v[32:35], v[80:83], v[88:91], 0
	s_waitcnt vmcnt(26)
	v_mfma_f32_16x16x32_bf16 v[36:39], v[100:103], v[84:87], 0
	v_mfma_f32_16x16x32_bf16 v[52:55], v[96:99], v[92:95], v[52:55]
	s_waitcnt vmcnt(25)
	v_mfma_f32_16x16x32_bf16 v[32:35], v[96:99], v[104:107], v[32:35]
	v_mfma_f32_16x16x32_bf16 v[40:43], v[100:103], v[88:91], 0
	s_waitcnt vmcnt(24)
	v_mfma_f32_16x16x32_bf16 v[36:39], v[108:111], v[92:95], v[36:39]
	v_mfma_f32_16x16x32_bf16 v[40:43], v[108:111], v[104:107], v[40:43]
	s_waitcnt vmcnt(22)
	v_mfma_f32_16x16x32_bf16 v[52:55], v[112:115], v[116:119], v[52:55]
	s_waitcnt vmcnt(21)
	v_mfma_f32_16x16x32_bf16 v[32:35], v[112:115], v[120:123], v[32:35]
	s_waitcnt vmcnt(18)
	v_mfma_f32_16x16x32_bf16 v[36:39], v[132:135], v[116:119], v[36:39]
	v_mfma_f32_16x16x32_bf16 v[44:47], v[128:131], v[124:127], v[52:55]
	s_nop 2
	v_mfma_f32_16x16x32_bf16 v[40:43], v[132:135], v[120:123], v[40:43]
	s_waitcnt vmcnt(17)
	v_mfma_f32_16x16x32_bf16 v[32:35], v[128:131], v[144:147], v[32:35]
	s_waitcnt vmcnt(16)
	v_mfma_f32_16x16x32_bf16 v[36:39], v[148:151], v[124:127], v[36:39]
	v_mfma_f32_16x16x32_bf16 v[40:43], v[148:151], v[144:147], v[40:43]
	s_waitcnt vmcnt(14)
	v_mfma_f32_16x16x32_bf16 v[44:47], v[152:155], v[156:159], v[44:47]
	s_waitcnt vmcnt(13)
	v_mfma_f32_16x16x32_bf16 v[32:35], v[152:155], v[160:163], v[32:35]
	s_waitcnt vmcnt(10)
	v_mfma_f32_16x16x32_bf16 v[40:43], v[176:179], v[160:163], v[40:43]
	v_mfma_f32_16x16x32_bf16 v[36:39], v[176:179], v[156:159], v[36:39]
	v_mfma_f32_16x16x32_bf16 v[44:47], v[168:171], v[164:167], v[44:47]
	s_waitcnt vmcnt(9)
	v_mfma_f32_16x16x32_bf16 v[32:35], v[168:171], v[180:183], v[32:35]
	s_waitcnt vmcnt(8)
	v_mfma_f32_16x16x32_bf16 v[36:39], v[184:187], v[164:167], v[36:39]
	v_mfma_f32_16x16x32_bf16 v[40:43], v[184:187], v[180:183], v[40:43]
	s_waitcnt vmcnt(6)
	v_mfma_f32_16x16x32_bf16 v[44:47], v[188:191], v[192:195], v[44:47]
	s_waitcnt vmcnt(5)
	v_mfma_f32_16x16x32_bf16 v[32:35], v[188:191], v[196:199], v[32:35]
	s_barrier
	s_waitcnt vmcnt(2)
	v_mfma_f32_16x16x32_bf16 v[36:39], v[208:211], v[192:195], v[36:39]
	v_mfma_f32_16x16x32_bf16 v[40:43], v[208:211], v[196:199], v[40:43]
	v_mfma_f32_16x16x32_bf16 v[44:47], v[204:207], v[200:203], v[44:47]
	s_waitcnt vmcnt(1)
	v_mfma_f32_16x16x32_bf16 v[32:35], v[204:207], v[212:215], v[32:35]
	s_nop 5
	ds_write_b128 v30, v[44:47]
	s_nop 0
	ds_write_b128 v30, v[32:35] offset:32
	s_waitcnt vmcnt(0)
	v_mfma_f32_16x16x32_bf16 v[36:39], v[216:219], v[200:203], v[36:39]
	v_mfma_f32_16x16x32_bf16 v[32:35], v[216:219], v[212:215], v[40:43]
	s_nop 6
	ds_write_b128 v30, v[36:39] offset:16
	ds_write_b128 v30, v[32:35] offset:48
	s_waitcnt lgkmcnt(0)
	s_barrier
	s_cbranch_vccnz .LBB0_1270
	v_lshl_or_b32 v2, s10, 8, v140
	v_or_b32_e32 v2, s11, v2
	v_lshlrev_b32_e32 v2, 1, v2
	v_lshl_add_u64 v[32:33], v[4:5], 0, v[2:3]
	global_load_dwordx4 v[32:35], v[32:33], off
	ds_read_b128 v[36:39], v31
	ds_read_b128 v[40:43], v31 offset:16
	ds_read_b128 v[44:47], v31 offset:4096
	ds_read_b128 v[48:51], v31 offset:4112
	ds_read_b128 v[52:55], v31 offset:8192
	ds_read_b128 v[56:59], v31 offset:8208
	ds_read_b128 v[60:63], v31 offset:12288
	ds_read_b128 v[64:67], v31 offset:12304
	ds_read_b128 v[68:71], v31 offset:16384
	ds_read_b128 v[72:75], v31 offset:16400
	ds_read_b128 v[76:79], v31 offset:20480
	ds_read_b128 v[80:83], v31 offset:20496
	ds_read_b128 v[84:87], v31 offset:24576
	ds_read_b128 v[88:91], v31 offset:24592
	ds_read_b128 v[92:95], v31 offset:28672
	ds_read_b128 v[96:99], v31 offset:28688
	s_waitcnt lgkmcnt(14)
	v_pk_add_f32 v[38:39], v[38:39], 0 op_sel_hi:[1,0]
	v_pk_add_f32 v[36:37], v[36:37], 0 op_sel_hi:[1,0]
	v_pk_add_f32 v[42:43], v[42:43], 0 op_sel_hi:[1,0]
	v_pk_add_f32 v[40:41], v[40:41], 0 op_sel_hi:[1,0]
	s_waitcnt lgkmcnt(13)
	v_pk_add_f32 v[38:39], v[38:39], v[46:47]
	v_pk_add_f32 v[36:37], v[36:37], v[44:45]
	s_waitcnt lgkmcnt(12)
	v_pk_add_f32 v[42:43], v[42:43], v[50:51]
	v_pk_add_f32 v[40:41], v[40:41], v[48:49]
	s_waitcnt lgkmcnt(11)
	v_pk_add_f32 v[38:39], v[38:39], v[54:55]
	v_pk_add_f32 v[36:37], v[36:37], v[52:53]
	s_waitcnt lgkmcnt(10)
	v_pk_add_f32 v[42:43], v[42:43], v[58:59]
	v_pk_add_f32 v[40:41], v[40:41], v[56:57]
	s_waitcnt lgkmcnt(9)
	v_pk_add_f32 v[38:39], v[38:39], v[62:63]
	v_pk_add_f32 v[36:37], v[36:37], v[60:61]
	s_waitcnt lgkmcnt(8)
	v_pk_add_f32 v[42:43], v[42:43], v[66:67]
	v_pk_add_f32 v[40:41], v[40:41], v[64:65]
	s_waitcnt lgkmcnt(7)
	v_pk_add_f32 v[38:39], v[38:39], v[70:71]
	v_pk_add_f32 v[36:37], v[36:37], v[68:69]
	s_waitcnt lgkmcnt(6)
	v_pk_add_f32 v[42:43], v[42:43], v[74:75]
	v_pk_add_f32 v[40:41], v[40:41], v[72:73]
	s_waitcnt lgkmcnt(5)
	v_pk_add_f32 v[38:39], v[38:39], v[78:79]
	v_pk_add_f32 v[36:37], v[36:37], v[76:77]
	s_waitcnt lgkmcnt(4)
	v_pk_add_f32 v[42:43], v[42:43], v[82:83]
	v_pk_add_f32 v[40:41], v[40:41], v[80:81]
	s_waitcnt lgkmcnt(3)
	v_pk_add_f32 v[38:39], v[38:39], v[86:87]
	v_pk_add_f32 v[36:37], v[36:37], v[84:85]
	s_waitcnt lgkmcnt(2)
	v_pk_add_f32 v[42:43], v[42:43], v[90:91]
	v_pk_add_f32 v[40:41], v[40:41], v[88:89]
	s_waitcnt lgkmcnt(1)
	v_pk_add_f32 v[38:39], v[38:39], v[94:95]
	v_pk_add_f32 v[36:37], v[36:37], v[92:93]
	s_waitcnt lgkmcnt(0)
	v_pk_add_f32 v[42:43], v[42:43], v[98:99]
	v_pk_add_f32 v[40:41], v[40:41], v[96:97]
	s_waitcnt vmcnt(0)
	v_lshlrev_b32_e32 v44, 16, v32
	v_and_b32_e32 v45, 0xffff0000, v32
	v_lshlrev_b32_e32 v32, 16, v33
	v_and_b32_e32 v33, 0xffff0000, v33
	v_lshlrev_b32_e32 v46, 16, v34
	v_and_b32_e32 v47, 0xffff0000, v34
	v_lshlrev_b32_e32 v34, 16, v35
	v_and_b32_e32 v35, 0xffff0000, v35
	v_pk_add_f32 v[36:37], v[36:37], v[44:45]
	v_pk_add_f32 v[38:39], v[38:39], v[32:33]
	v_pk_add_f32 v[40:41], v[40:41], v[46:47]
	v_pk_add_f32 v[42:43], v[42:43], v[34:35]
	v_cvt_pk_bf16_f32 v32, v36, v37
	v_cvt_pk_bf16_f32 v33, v38, v39
	v_cvt_pk_bf16_f32 v34, v40, v41
	v_cvt_pk_bf16_f32 v35, v42, v43
	v_lshl_add_u64 v[36:37], v[6:7], 0, v[2:3]
	global_store_dwordx4 v[36:37], v[32:35], off
	s_branch .LBB0_1270

.LBB0_1356:
	s_lshr_b32 s10, s3, 3
	s_and_b32 s11, s1, 0xe0
	s_lshl_b32 s12, s10, 20
	s_add_u32 s12, s34, s12
	s_addc_u32 s13, s35, 0
	s_lshl_b32 s14, s11, 12
	s_add_u32 s12, s12, s14
	s_addc_u32 s13, s13, 0
	s_add_u32 s12, s12, s4
	s_addc_u32 s13, s13, s5
	v_lshl_add_u64 v[32:33], s[12:13], 0, v[26:27]
	v_lshl_add_u64 v[76:77], v[32:33], 0, v[28:29]
	v_add_co_u32_e32 v78, vcc, s0, v76
	s_nop 1
	v_addc_co_u32_e32 v79, vcc, 0, v77, vcc
	s_and_b64 vcc, exec, s[6:7]
	global_load_dwordx4 v[80:83], v[76:77], off
	global_load_dwordx4 v[84:87], v[2:3], off
	global_load_dwordx4 v[88:91], v[4:5], off
	global_load_dwordx4 v[92:95], v[2:3], off offset:64
	global_load_dwordx4 v[96:99], v[76:77], off offset:64
	global_load_dwordx4 v[100:103], v[78:79], off
	global_load_dwordx4 v[104:107], v[6:7], off
	global_load_dwordx4 v[108:111], v[78:79], off offset:64
	global_load_dwordx4 v[112:115], v[76:77], off offset:128
	global_load_dwordx4 v[116:119], v[2:3], off offset:128
	global_load_dwordx4 v[120:123], v[8:9], off
	global_load_dwordx4 v[124:127], v[2:3], off offset:192
	global_load_dwordx4 v[132:135], v[76:77], off offset:192
	global_load_dwordx4 v[140:143], v[78:79], off offset:128
	global_load_dwordx4 v[144:147], v[10:11], off
	global_load_dwordx4 v[148:151], v[78:79], off offset:192
	global_load_dwordx4 v[152:155], v[76:77], off offset:256
	global_load_dwordx4 v[156:159], v[2:3], off offset:256
	global_load_dwordx4 v[160:163], v[12:13], off
	global_load_dwordx4 v[164:167], v[2:3], off offset:320
	global_load_dwordx4 v[168:171], v[76:77], off offset:320
	global_load_dwordx4 v[172:175], v[78:79], off offset:256
	global_load_dwordx4 v[176:179], v[14:15], off
	global_load_dwordx4 v[180:183], v[78:79], off offset:320
	global_load_dwordx4 v[184:187], v[76:77], off offset:384
	global_load_dwordx4 v[188:191], v[2:3], off offset:384
	global_load_dwordx4 v[192:195], v[16:17], off
	global_load_dwordx4 v[196:199], v[2:3], off offset:448
	global_load_dwordx4 v[200:203], v[76:77], off offset:448
	global_load_dwordx4 v[204:207], v[78:79], off offset:384
	global_load_dwordx4 v[208:211], v[18:19], off
	global_load_dwordx4 v[212:215], v[78:79], off offset:448
	s_waitcnt vmcnt(30)
	v_mfma_f32_16x16x32_bf16 v[52:55], v[80:83], v[84:87], 0
	s_waitcnt vmcnt(29)
	v_mfma_f32_16x16x32_bf16 v[32:35], v[80:83], v[88:91], 0
	s_waitcnt vmcnt(26)
	v_mfma_f32_16x16x32_bf16 v[36:39], v[100:103], v[84:87], 0
	v_mfma_f32_16x16x32_bf16 v[52:55], v[96:99], v[92:95], v[52:55]
	s_waitcnt vmcnt(25)
	v_mfma_f32_16x16x32_bf16 v[32:35], v[96:99], v[104:107], v[32:35]
	v_mfma_f32_16x16x32_bf16 v[40:43], v[100:103], v[88:91], 0
	s_waitcnt vmcnt(24)
	v_mfma_f32_16x16x32_bf16 v[36:39], v[108:111], v[92:95], v[36:39]
	v_mfma_f32_16x16x32_bf16 v[40:43], v[108:111], v[104:107], v[40:43]
	s_waitcnt vmcnt(22)
	v_mfma_f32_16x16x32_bf16 v[52:55], v[112:115], v[116:119], v[52:55]
	s_waitcnt vmcnt(21)
	v_mfma_f32_16x16x32_bf16 v[32:35], v[112:115], v[120:123], v[32:35]
	s_waitcnt vmcnt(18)
	v_mfma_f32_16x16x32_bf16 v[36:39], v[140:143], v[116:119], v[36:39]
	v_mfma_f32_16x16x32_bf16 v[44:47], v[132:135], v[124:127], v[52:55]
	s_nop 2
	v_mfma_f32_16x16x32_bf16 v[40:43], v[140:143], v[120:123], v[40:43]
	s_waitcnt vmcnt(17)
	v_mfma_f32_16x16x32_bf16 v[32:35], v[132:135], v[144:147], v[32:35]
	s_waitcnt vmcnt(16)
	v_mfma_f32_16x16x32_bf16 v[36:39], v[148:151], v[124:127], v[36:39]
	v_mfma_f32_16x16x32_bf16 v[40:43], v[148:151], v[144:147], v[40:43]
	s_waitcnt vmcnt(14)
	v_mfma_f32_16x16x32_bf16 v[44:47], v[152:155], v[156:159], v[44:47]
	s_waitcnt vmcnt(13)
	v_mfma_f32_16x16x32_bf16 v[32:35], v[152:155], v[160:163], v[32:35]
	s_waitcnt vmcnt(10)
	v_mfma_f32_16x16x32_bf16 v[40:43], v[172:175], v[160:163], v[40:43]
	v_mfma_f32_16x16x32_bf16 v[36:39], v[172:175], v[156:159], v[36:39]
	v_mfma_f32_16x16x32_bf16 v[44:47], v[168:171], v[164:167], v[44:47]
	s_waitcnt vmcnt(9)
	v_mfma_f32_16x16x32_bf16 v[32:35], v[168:171], v[176:179], v[32:35]
	s_waitcnt vmcnt(8)
	v_mfma_f32_16x16x32_bf16 v[36:39], v[180:183], v[164:167], v[36:39]
	v_mfma_f32_16x16x32_bf16 v[40:43], v[180:183], v[176:179], v[40:43]
	s_waitcnt vmcnt(6)
	v_mfma_f32_16x16x32_bf16 v[44:47], v[184:187], v[188:191], v[44:47]
	s_waitcnt vmcnt(5)
	v_mfma_f32_16x16x32_bf16 v[32:35], v[184:187], v[192:195], v[32:35]
	s_barrier
	s_waitcnt vmcnt(2)
	v_mfma_f32_16x16x32_bf16 v[36:39], v[204:207], v[188:191], v[36:39]
	v_mfma_f32_16x16x32_bf16 v[40:43], v[204:207], v[192:195], v[40:43]
	v_mfma_f32_16x16x32_bf16 v[44:47], v[200:203], v[196:199], v[44:47]
	s_waitcnt vmcnt(1)
	v_mfma_f32_16x16x32_bf16 v[32:35], v[200:203], v[208:211], v[32:35]
	s_nop 5
	ds_write_b128 v30, v[44:47]
	s_nop 0
	ds_write_b128 v30, v[32:35] offset:32
	s_waitcnt vmcnt(0)
	v_mfma_f32_16x16x32_bf16 v[36:39], v[212:215], v[196:199], v[36:39]
	v_mfma_f32_16x16x32_bf16 v[32:35], v[212:215], v[208:211], v[40:43]
	s_nop 6
	ds_write_b128 v30, v[36:39] offset:16
	ds_write_b128 v30, v[32:35] offset:48
	s_waitcnt lgkmcnt(0)
	s_barrier
	s_cbranch_vccnz .LBB0_1355
	ds_read_b128 v[32:35], v31
	ds_read_b128 v[36:39], v31 offset:16
	v_lshl_or_b32 v0, s10, 8, v130
	v_or_b32_e32 v0, s11, v0
	v_lshlrev_b32_e32 v0, 1, v0
	s_waitcnt lgkmcnt(1)
	v_pk_add_f32 v[52:53], v[34:35], 0 op_sel_hi:[1,0]
	v_lshl_add_u64 v[34:35], v[20:21], 0, v[0:1]
	global_load_dwordx4 v[40:43], v[34:35], off
	v_lshl_add_u64 v[34:35], v[22:23], 0, v[0:1]
	global_load_dwordx4 v[44:47], v[34:35], off
	ds_read_b128 v[48:51], v31 offset:4096
	v_pk_add_f32 v[54:55], v[32:33], 0 op_sel_hi:[1,0]
	ds_read_b128 v[32:35], v31 offset:4112
	s_waitcnt lgkmcnt(2)
	v_pk_add_f32 v[56:57], v[38:39], 0 op_sel_hi:[1,0]
	v_pk_add_f32 v[58:59], v[36:37], 0 op_sel_hi:[1,0]
	ds_read_b128 v[36:39], v31 offset:8192
	s_waitcnt lgkmcnt(2)
	v_pk_add_f32 v[52:53], v[52:53], v[50:51]
	v_pk_add_f32 v[54:55], v[54:55], v[48:49]
	s_waitcnt lgkmcnt(1)
	v_pk_add_f32 v[56:57], v[56:57], v[34:35]
	ds_read_b128 v[48:51], v31 offset:8208
	v_pk_add_f32 v[58:59], v[58:59], v[32:33]
	ds_read_b128 v[32:35], v31 offset:12288
	s_waitcnt lgkmcnt(2)
	v_pk_add_f32 v[52:53], v[52:53], v[38:39]
	v_pk_add_f32 v[54:55], v[54:55], v[36:37]
	ds_read_b128 v[36:39], v31 offset:12304
	s_waitcnt lgkmcnt(2)
	v_pk_add_f32 v[56:57], v[56:57], v[50:51]
	v_pk_add_f32 v[58:59], v[58:59], v[48:49]
	s_waitcnt lgkmcnt(1)
	v_pk_add_f32 v[52:53], v[52:53], v[34:35]
	ds_read_b128 v[48:51], v31 offset:16384
	v_pk_add_f32 v[54:55], v[54:55], v[32:33]
	ds_read_b128 v[32:35], v31 offset:16400
	s_waitcnt lgkmcnt(2)
	v_pk_add_f32 v[56:57], v[56:57], v[38:39]
	v_pk_add_f32 v[58:59], v[58:59], v[36:37]
	ds_read_b128 v[36:39], v31 offset:20480
	s_waitcnt lgkmcnt(2)
	v_pk_add_f32 v[52:53], v[52:53], v[50:51]
	v_pk_add_f32 v[54:55], v[54:55], v[48:49]
	s_waitcnt lgkmcnt(1)
	v_pk_add_f32 v[56:57], v[56:57], v[34:35]
	ds_read_b128 v[48:51], v31 offset:20496
	v_pk_add_f32 v[58:59], v[58:59], v[32:33]
	ds_read_b128 v[32:35], v31 offset:24576
	s_waitcnt lgkmcnt(2)
	v_pk_add_f32 v[52:53], v[52:53], v[38:39]
	v_pk_add_f32 v[54:55], v[54:55], v[36:37]
	ds_read_b128 v[36:39], v31 offset:24592
	s_waitcnt lgkmcnt(2)
	v_pk_add_f32 v[56:57], v[56:57], v[50:51]
	v_pk_add_f32 v[58:59], v[58:59], v[48:49]
	s_waitcnt lgkmcnt(1)
	v_pk_add_f32 v[52:53], v[52:53], v[34:35]
	ds_read_b128 v[48:51], v31 offset:28672
	v_pk_add_f32 v[54:55], v[54:55], v[32:33]
	ds_read_b128 v[32:35], v31 offset:28688
	s_waitcnt lgkmcnt(2)
	v_pk_add_f32 v[36:37], v[58:59], v[36:37]
	v_pk_add_f32 v[38:39], v[56:57], v[38:39]
	s_waitcnt lgkmcnt(1)
	v_pk_add_f32 v[48:49], v[54:55], v[48:49]
	v_pk_add_f32 v[50:51], v[52:53], v[50:51]
	s_waitcnt lgkmcnt(0)
	v_pk_add_f32 v[32:33], v[36:37], v[32:33]
	v_mul_f32_e32 v36, 0xbfb8aa3b, v48
	v_mul_f32_e32 v32, 0xbfb8aa3b, v32
	v_exp_f32_e32 v36, v36
	v_exp_f32_e32 v37, v32
	v_mul_f32_e32 v33, 0xbfb8aa3b, v33
	v_pk_add_f32 v[34:35], v[38:39], v[34:35]
	v_add_f32_e32 v32, 1.0, v36
	v_add_f32_e32 v36, 1.0, v37
	v_mul_f32_e32 v37, 0xbfb8aa3b, v49
	v_exp_f32_e32 v37, v37
	v_exp_f32_e32 v38, v33
	v_mul_f32_e32 v34, 0xbfb8aa3b, v34
	v_exp_f32_e32 v39, v34
	v_add_f32_e32 v33, 1.0, v37
	v_add_f32_e32 v37, 1.0, v38
	v_mul_f32_e32 v38, 0xbfb8aa3b, v50
	v_exp_f32_e32 v38, v38
	v_mul_f32_e32 v35, 0xbfb8aa3b, v35
	v_exp_f32_e32 v48, v35
	v_rcp_f32_e32 v36, v36
	v_add_f32_e32 v34, 1.0, v38
	v_add_f32_e32 v38, 1.0, v39
	v_mul_f32_e32 v39, 0xbfb8aa3b, v51
	v_exp_f32_e32 v39, v39
	v_rcp_f32_e32 v34, v34
	v_rcp_f32_e32 v37, v37
	v_rcp_f32_e32 v32, v32
	v_add_f32_e32 v35, 1.0, v39
	v_rcp_f32_e32 v35, v35
	v_add_f32_e32 v39, 1.0, v48
	v_rcp_f32_e32 v33, v33
	v_rcp_f32_e32 v38, v38
	v_rcp_f32_e32 v39, v39
	s_waitcnt vmcnt(1)
	v_lshlrev_b32_e32 v48, 16, v40
	v_and_b32_e32 v49, 0xffff0000, v40
	s_waitcnt vmcnt(0)
	v_lshlrev_b32_e32 v50, 16, v44
	v_and_b32_e32 v51, 0xffff0000, v44
	v_lshlrev_b32_e32 v40, 16, v41
	v_and_b32_e32 v41, 0xffff0000, v41
	v_lshlrev_b32_e32 v44, 16, v45
	v_and_b32_e32 v45, 0xffff0000, v45
	v_pk_fma_f32 v[34:35], v[34:35], v[40:41], v[44:45]
	v_lshlrev_b32_e32 v40, 16, v42
	v_and_b32_e32 v41, 0xffff0000, v42
	v_lshlrev_b32_e32 v44, 16, v46
	v_and_b32_e32 v45, 0xffff0000, v46
	v_pk_fma_f32 v[36:37], v[36:37], v[40:41], v[44:45]
	v_lshlrev_b32_e32 v40, 16, v43
	v_and_b32_e32 v41, 0xffff0000, v43
	v_lshlrev_b32_e32 v42, 16, v47
	v_and_b32_e32 v43, 0xffff0000, v47
	v_pk_fma_f32 v[32:33], v[32:33], v[48:49], v[50:51]
	v_pk_fma_f32 v[38:39], v[38:39], v[40:41], v[42:43]
	v_cvt_pk_bf16_f32 v32, v32, v33
	v_cvt_pk_bf16_f32 v33, v34, v35
	v_cvt_pk_bf16_f32 v34, v36, v37
	v_cvt_pk_bf16_f32 v35, v38, v39
	v_lshl_add_u64 v[36:37], v[24:25], 0, v[0:1]
	global_store_dwordx4 v[36:37], v[32:35], off
	s_branch .LBB0_1355
